# attention: LDS staging of the prefetched K/V tile moved from the PV(A) gaps to the PV(B) gaps
# speedup vs baseline: 1.0108x; 1.0014x over previous
; #define LAS __attribute__((address_space(3)))
; __device__ __forceinline__ void attn_pv(const bf16x8 (&vf)[8], const bf16x8 (&pb)[4], f32x16& o0, f32x16& o1) {
; #pragma unroll
;     for (int s = 0; s < 4; ++s) {
;         o0 = __builtin_amdgcn_mfma_f32_32x32x16_bf16(vf[2 * s], pb[s], o0, 0, 0, 0);
;         o1 = __builtin_amdgcn_mfma_f32_32x32x16_bf16(vf[2 * s + 1], pb[s], o1, 0, 0, 0);
;     }
; }
; __device__ __forceinline__ void attn_phase(LAS unsigned char* lds, const bf16_t* __restrict__ Q, const bf16_t* __restrict__ KN, const bf16_t* __restrict__ KR,
;                                            const bf16_t* __restrict__ VT, bf16_t* AO, int vcu, int G, int tid, int lane, int wave) {
;     ...
;                     attn_softmax(a0, a1, pa, o0, o1, m_run, l_run);
;                     attn_ldv(vf, vA);
;                     __builtin_amdgcn_sched_barrier(0);
;                     PREFETCH_NEXT();
;                     attn_ldv(vf2, vA + 128);
;                     __builtin_amdgcn_sched_barrier(0);
;                     attn_pv(vf, pa, o0, o1);
;                     attn_softmax(b0, b1, pb2, o0, o1, m_run, l_run);
;                     __builtin_amdgcn_sched_barrier(0);
;                     attn_pv(vf2, pb2, o0, o1);
;                 } else if (2 * t <= qc) {
;                     bf16x8 kf[12], vf[8], pa[4]; f32x16 a0, a1;
;                     PREFETCH_NEXT();
;                     attn_ldk(kf, kA);
;                     __builtin_amdgcn_sched_barrier(0);
;                     attn_qk(a0, a1, kf, qf);
;                     __builtin_amdgcn_sched_barrier(0);
;                     attn_ldv(vf, vA);
;                     __builtin_amdgcn_sched_barrier(0);
;                     attn_softmax(a0, a1, pa, o0, o1, m_run, l_run);
;                     __builtin_amdgcn_sched_barrier(0);
;                     attn_pv(vf, pa, o0, o1);
;                 } else { PREFETCH_NEXT(); }
;                 if (more) { LAS unsigned char* nb = lds + ((t + 1) & 1) * BUF;
;                     *(LAS u32x4*)(nb + kdst) = gk0; *(LAS u32x4*)(nb + kdst + 64 * KP * 2) = gk1; *(LAS u32x4*)(nb + rdst) = gr; *(LAS u32x4*)(nb + vdst) = gv0; *(LAS u32x4*)(nb + vdst + 128) = gv1; }
.Lat_fast_A2:
	v_add_f32_e32 v227, v227, v1
	v_cvt_pk_bf16_f32 v34, v34, v35
	v_cvt_pk_bf16_f32 v35, v36, v37
	v_cvt_pk_bf16_f32 v36, v38, v39
	v_cvt_pk_bf16_f32 v37, v40, v41
	v_cvt_pk_bf16_f32 v42, v42, v43
	v_cvt_pk_bf16_f32 v43, v44, v45
	v_cvt_pk_bf16_f32 v44, v46, v47
	v_cvt_pk_bf16_f32 v45, v48, v49
	v_cvt_pk_bf16_f32 v50, v50, v51
	v_cvt_pk_bf16_f32 v51, v52, v53
	v_cvt_pk_bf16_f32 v52, v54, v55
	v_cvt_pk_bf16_f32 v53, v56, v57
	v_cvt_pk_bf16_f32 v58, v58, v59
	v_cvt_pk_bf16_f32 v59, v60, v61
	v_cvt_pk_bf16_f32 v60, v62, v63
	v_cvt_pk_bf16_f32 v61, v64, v65
	s_cmp_lg_u32 s6, 0
	s_cbranch_scc1 .Lat_plain_B2
	s_cmp_lg_u32 s7, 0
	s_cbranch_scc1 .Lat_plain_B2
	s_waitcnt lgkmcnt(5)
	v_mfma_f32_32x32x16_bf16 v[2:17], v[170:173], v[34:37], v[2:17]
	ds_read_b128 v[170:173], v225 offset:26720
	v_exp_f32_e32 v66, v66
	v_exp_f32_e32 v82, v82
	v_exp_f32_e32 v67, v67
	v_exp_f32_e32 v83, v83
	s_waitcnt lgkmcnt(5)
	v_mfma_f32_32x32x16_bf16 v[18:33], v[174:177], v[34:37], v[18:33]
	ds_read_b128 v[174:177], v225 offset:35424
	v_exp_f32_e32 v68, v68
	v_exp_f32_e32 v84, v84
	v_exp_f32_e32 v69, v69
	v_exp_f32_e32 v85, v85
	s_waitcnt lgkmcnt(5)
	v_mfma_f32_32x32x16_bf16 v[2:17], v[178:181], v[42:45], v[2:17]
	ds_read_b128 v[178:181], v225 offset:26752
	v_exp_f32_e32 v70, v70
	v_exp_f32_e32 v86, v86
	v_exp_f32_e32 v71, v71
	v_exp_f32_e32 v87, v87
	s_waitcnt lgkmcnt(5)
	v_mfma_f32_32x32x16_bf16 v[18:33], v[182:185], v[42:45], v[18:33]
	ds_read_b128 v[182:185], v225 offset:35456
	v_exp_f32_e32 v72, v72
	v_exp_f32_e32 v88, v88
	v_exp_f32_e32 v73, v73
	v_exp_f32_e32 v89, v89
	s_waitcnt lgkmcnt(5)
	v_mfma_f32_32x32x16_bf16 v[2:17], v[186:189], v[50:53], v[2:17]
	ds_read_b128 v[186:189], v225 offset:26784
	v_exp_f32_e32 v74, v74
	v_exp_f32_e32 v90, v90
	v_exp_f32_e32 v75, v75
	v_exp_f32_e32 v91, v91
	s_waitcnt lgkmcnt(5)
	v_mfma_f32_32x32x16_bf16 v[18:33], v[190:193], v[50:53], v[18:33]
	ds_read_b128 v[190:193], v225 offset:35488
	v_exp_f32_e32 v76, v76
	v_exp_f32_e32 v92, v92
	v_exp_f32_e32 v77, v77
	v_exp_f32_e32 v93, v93
	s_waitcnt lgkmcnt(5)
	v_mfma_f32_32x32x16_bf16 v[2:17], v[170:173], v[58:61], v[2:17]
	ds_read_b128 v[170:173], v225 offset:26816
	v_exp_f32_e32 v78, v78
	v_exp_f32_e32 v94, v94
	v_exp_f32_e32 v79, v79
	v_exp_f32_e32 v95, v95
	s_waitcnt lgkmcnt(5)
	v_mfma_f32_32x32x16_bf16 v[18:33], v[174:177], v[58:61], v[18:33]
	ds_read_b128 v[174:177], v225 offset:35520
	v_exp_f32_e32 v80, v80
	v_exp_f32_e32 v96, v96
	v_exp_f32_e32 v81, v81
	v_exp_f32_e32 v97, v97
	s_mov_b32 s41, 0
	s_branch .Lat_sum_B2
.Lat_plain_B2:
	s_waitcnt lgkmcnt(5)
	v_mfma_f32_32x32x16_bf16 v[2:17], v[170:173], v[34:37], v[2:17]
	ds_read_b128 v[170:173], v225 offset:26720
	s_waitcnt lgkmcnt(5)
	v_mfma_f32_32x32x16_bf16 v[18:33], v[174:177], v[34:37], v[18:33]
	ds_read_b128 v[174:177], v225 offset:35424
	s_waitcnt lgkmcnt(5)
	v_mfma_f32_32x32x16_bf16 v[2:17], v[178:181], v[42:45], v[2:17]
	ds_read_b128 v[178:181], v225 offset:26752
	s_waitcnt lgkmcnt(5)
	v_mfma_f32_32x32x16_bf16 v[18:33], v[182:185], v[42:45], v[18:33]
	ds_read_b128 v[182:185], v225 offset:35456
	s_waitcnt lgkmcnt(5)
	v_mfma_f32_32x32x16_bf16 v[2:17], v[186:189], v[50:53], v[2:17]
	ds_read_b128 v[186:189], v225 offset:26784
	s_waitcnt lgkmcnt(5)
	v_mfma_f32_32x32x16_bf16 v[18:33], v[190:193], v[50:53], v[18:33]
	ds_read_b128 v[190:193], v225 offset:35488
	s_waitcnt lgkmcnt(5)
	v_mfma_f32_32x32x16_bf16 v[2:17], v[170:173], v[58:61], v[2:17]
	ds_read_b128 v[170:173], v225 offset:26816
	s_waitcnt lgkmcnt(5)
	v_mfma_f32_32x32x16_bf16 v[18:33], v[174:177], v[58:61], v[18:33]
	ds_read_b128 v[174:177], v225 offset:35520
	s_cmp_lg_u32 s6, 0
	s_cbranch_scc1 .Lat_fix_B

; __device__ __forceinline__ void attn_softmax(f32x16& p0, f32x16& p1, bf16x8 (&pb)[4], f32x16& o0, f32x16& o1, float& m_run, float& l_run) {
;     ...
;         u32x4 w; w.x = pk2(p0[8 * s], p0[8 * s + 1]); w.y = pk2(p0[8 * s + 2], p0[8 * s + 3]); w.z = pk2(p0[8 * s + 4], p0[8 * s + 5]); w.w = pk2(p0[8 * s + 6], p0[8 * s + 7]);
;         pb[s] = __builtin_bit_cast(bf16x8, w);
;         u32x4 w2; w2.x = pk2(p1[8 * s], p1[8 * s + 1]); w2.y = pk2(p1[8 * s + 2], p1[8 * s + 3]); w2.z = pk2(p1[8 * s + 4], p1[8 * s + 5]); w2.w = pk2(p1[8 * s + 6], p1[8 * s + 7]);
;         pb[2 + s] = __builtin_bit_cast(bf16x8, w2);
;     }
; }
; __device__ __forceinline__ void attn_pv(const bf16x8 (&vf)[8], const bf16x8 (&pb)[4], f32x16& o0, f32x16& o1) {
; #pragma unroll
;     for (int s = 0; s < 4; ++s) {
; __device__ __forceinline__ void attn_phase(LAS unsigned char* lds, const bf16_t* __restrict__ Q, const bf16_t* __restrict__ KN, const bf16_t* __restrict__ KR,
;                                            const bf16_t* __restrict__ VT, bf16_t* AO, int vcu, int G, int tid, int lane, int wave) {
;     ...
;                     attn_ldv(vf2, vA + 128);
;                     __builtin_amdgcn_sched_barrier(0);
;                     attn_pv(vf, pa, o0, o1);
;                     attn_softmax(b0, b1, pb2, o0, o1, m_run, l_run);
;                     __builtin_amdgcn_sched_barrier(0);
;                     attn_pv(vf2, pb2, o0, o1);
;                 } else if (2 * t <= qc) {
;                     bf16x8 kf[12], vf[8], pa[4]; f32x16 a0, a1;
;                     PREFETCH_NEXT();
;                     attn_ldk(kf, kA);
;                     __builtin_amdgcn_sched_barrier(0);
;                     attn_qk(a0, a1, kf, qf);
;                     __builtin_amdgcn_sched_barrier(0);
;                     attn_ldv(vf, vA);
;                     __builtin_amdgcn_sched_barrier(0);
;                     attn_softmax(a0, a1, pa, o0, o1, m_run, l_run);
;                     __builtin_amdgcn_sched_barrier(0);
;                     attn_pv(vf, pa, o0, o1);
;                 } else { PREFETCH_NEXT(); }
;                 if (more) { LAS unsigned char* nb = lds + ((t + 1) & 1) * BUF;
;                     *(LAS u32x4*)(nb + kdst) = gk0; *(LAS u32x4*)(nb + kdst + 64 * KP * 2) = gk1; *(LAS u32x4*)(nb + rdst) = gr; *(LAS u32x4*)(nb + vdst) = gv0; *(LAS u32x4*)(nb + vdst + 128) = gv1; }
.Lat_fast_B2:
	v_add_f32_e32 v227, v227, v1
	v_cvt_pk_bf16_f32 v66, v66, v67
	v_cvt_pk_bf16_f32 v67, v68, v69
	v_cvt_pk_bf16_f32 v68, v70, v71
	v_cvt_pk_bf16_f32 v69, v72, v73
	v_cvt_pk_bf16_f32 v74, v74, v75
	v_cvt_pk_bf16_f32 v75, v76, v77
	v_cvt_pk_bf16_f32 v76, v78, v79
	v_cvt_pk_bf16_f32 v77, v80, v81
	v_cvt_pk_bf16_f32 v82, v82, v83
	v_cvt_pk_bf16_f32 v83, v84, v85
	v_cvt_pk_bf16_f32 v84, v86, v87
	v_cvt_pk_bf16_f32 v85, v88, v89
	v_cvt_pk_bf16_f32 v90, v90, v91
	v_cvt_pk_bf16_f32 v91, v92, v93
	v_cvt_pk_bf16_f32 v92, v94, v95
	v_cvt_pk_bf16_f32 v93, v96, v97
	s_waitcnt lgkmcnt(5)
	v_mfma_f32_32x32x16_bf16 v[2:17], v[178:181], v[66:69], v[2:17]
	ds_read_b128 v[178:181], v225 offset:26848
	s_waitcnt vmcnt(0)
	v_add_u32_e32 v226, s38, v219
	ds_write_b128 v226, v[228:231]
	s_waitcnt lgkmcnt(6)
	v_mfma_f32_32x32x16_bf16 v[18:33], v[182:185], v[66:69], v[18:33]
	ds_read_b128 v[182:185], v225 offset:35552
	ds_write_b128 v226, v[232:235] offset:13312
	s_waitcnt lgkmcnt(7)
	v_mfma_f32_32x32x16_bf16 v[2:17], v[186:189], v[74:77], v[2:17]
	v_add_u32_e32 v226, s38, v220
	ds_write_b128 v226, v[236:239]
	s_waitcnt lgkmcnt(7)
	v_mfma_f32_32x32x16_bf16 v[18:33], v[190:193], v[74:77], v[18:33]
	v_add_u32_e32 v226, s38, v221
	ds_write_b128 v226, v[240:243] offset:26624
	s_waitcnt lgkmcnt(7)
	v_mfma_f32_32x32x16_bf16 v[2:17], v[170:173], v[82:85], v[2:17]
	ds_write_b128 v226, v[244:247] offset:26752
	s_waitcnt lgkmcnt(7)
	v_mfma_f32_32x32x16_bf16 v[18:33], v[174:177], v[82:85], v[18:33]
	s_waitcnt lgkmcnt(6)
	v_mfma_f32_32x32x16_bf16 v[2:17], v[178:181], v[90:93], v[2:17]
	s_waitcnt lgkmcnt(4)
	v_mfma_f32_32x32x16_bf16 v[18:33], v[182:185], v[90:93], v[18:33]
	s_branch .Lat_nostage
